# RWKV next-block prefetch rewritten with wave-uniform SGPR bases and saddr loads (3 VALU instead of ~45 64-bit address adds per wave and block)
# speedup vs baseline: 1.0084x; 1.0013x over previous
.LBB0_564:
	v_mov_b32_e32 v78, v75
	v_mov_b32_e32 v76, v77
	s_and_b32 s3, s40, 1
	v_add_u32_e32 v28, s72, v76
	v_ashrrev_i32_e32 v29, 31, v28
	v_lshlrev_b64 v[10:11], 2, v[28:29]
	s_and_b32 s3, s40, 1
	s_mov_b32 s0, 0x17800
	s_mov_b32 s1, 0x1b800
	s_cmp_eq_u32 s3, 0
	s_cselect_b32 s41, 0x11800, s0
	s_cselect_b32 s16, 0x23800, s1
	v_lshlrev_b32_e32 v26, 3, v78
	v_mul_u32_u24_e32 v166, 0x880, v78
	v_lshl_add_u32 v166, v76, 2, v166
	v_lshlrev_b32_e32 v167, 11, v78
	v_lshl_add_u32 v167, v76, 2, v167
	v_add_u32_e32 v167, s41, v167
	v_mov_b32_e32 v140, 1.0
	v_sub_f32_e32 v169, v106, v44
	v_sub_f32_e32 v170, v35, v46
	v_sub_f32_e32 v171, v34, v48
	v_fma_f32 v169, v169, v115, v44
	v_fma_f32 v170, v170, v116, v46
	v_fma_f32 v171, v171, v119, v48
	v_add_f32_e32 v172, v50, v117
	v_add_f32_e32 v173, v107, v118
	v_mul_f32_e32 v172, 0xbfb8aa3b, v172
	v_mul_f32_e32 v173, 0xbfb8aa3b, v173
	v_exp_f32_e32 v172, v172
	v_exp_f32_e32 v173, v173
	ds_write_b32 v167, v171 offset:0
	v_add_f32_e32 v172, 1.0, v172
	v_add_f32_e32 v173, 1.0, v173
	v_rcp_f32_e32 v172, v172
	v_rcp_f32_e32 v173, v173
	v_mul_f32_e32 v124, v170, v120
	v_mul_f32_e32 v173, 0xbf1b4598, v173
	v_add_f32_e32 v174, -1.0, v172
	v_mul_f32_e32 v173, 0x3fb8aa3b, v173
	v_fma_f32 v174, v121, v174, 1.0
	v_exp_f32_e32 v173, v173
	v_mul_f32_e32 v174, v170, v174
	v_mul_f32_e32 v150, v124, v124
	v_mul_f32_e32 v175, v169, v174
	v_mul_f32_e32 v141, v140, v173
	v_mul_f32_e32 v158, v122, v175
	v_rcp_f32_e32 v176, v141
	v_mul_f32_e32 v169, v169, v141
	v_mul_f32_e32 v174, v174, v176
	v_mul_f32_e32 v132, v172, v176
	ds_write_b32 v166, v169 offset:17408
	ds_write_b32 v166, v174 offset:52224
	v_sub_f32_e32 v169, v44, v1
	v_sub_f32_e32 v170, v46, v45
	v_sub_f32_e32 v171, v48, v47
	v_fma_f32 v169, v169, v115, v1
	v_fma_f32 v170, v170, v116, v45
	v_fma_f32 v171, v171, v119, v47
	v_add_f32_e32 v172, v51, v117
	v_add_f32_e32 v173, v108, v118
	v_mul_f32_e32 v172, 0xbfb8aa3b, v172
	v_mul_f32_e32 v173, 0xbfb8aa3b, v173
	v_exp_f32_e32 v172, v172
	v_exp_f32_e32 v173, v173
	ds_write_b32 v167, v171 offset:256
	v_add_f32_e32 v172, 1.0, v172
	v_add_f32_e32 v173, 1.0, v173
	v_rcp_f32_e32 v172, v172
	v_rcp_f32_e32 v173, v173
	v_mul_f32_e32 v125, v170, v120
	v_mul_f32_e32 v173, 0xbf1b4598, v173
	v_add_f32_e32 v174, -1.0, v172
	v_mul_f32_e32 v173, 0x3fb8aa3b, v173
	v_fma_f32 v174, v121, v174, 1.0
	v_exp_f32_e32 v173, v173
	v_mul_f32_e32 v174, v170, v174
	v_mul_f32_e32 v152, v125, v125
	v_mul_f32_e32 v175, v169, v174
	v_mul_f32_e32 v142, v141, v173
	v_mul_f32_e32 v160, v122, v175
	v_rcp_f32_e32 v176, v142
	v_mul_f32_e32 v169, v169, v142
	v_mul_f32_e32 v174, v174, v176
	v_mul_f32_e32 v133, v172, v176
	ds_write_b32 v166, v169 offset:17680
	ds_write_b32 v166, v174 offset:52496
	v_sub_f32_e32 v169, v1, v52
	v_sub_f32_e32 v170, v45, v54
	v_sub_f32_e32 v171, v47, v56
	v_fma_f32 v169, v169, v115, v52
	v_fma_f32 v170, v170, v116, v54
	v_fma_f32 v171, v171, v119, v56
	v_add_f32_e32 v172, v58, v117
	v_add_f32_e32 v173, v109, v118
	v_mul_f32_e32 v172, 0xbfb8aa3b, v172
	v_mul_f32_e32 v173, 0xbfb8aa3b, v173
	v_exp_f32_e32 v172, v172
	v_exp_f32_e32 v173, v173
	ds_write_b32 v167, v171 offset:512
	v_add_f32_e32 v172, 1.0, v172
	v_add_f32_e32 v173, 1.0, v173
	v_rcp_f32_e32 v172, v172
	v_rcp_f32_e32 v173, v173
	v_mul_f32_e32 v126, v170, v120
	v_mul_f32_e32 v173, 0xbf1b4598, v173
	v_add_f32_e32 v174, -1.0, v172
	v_mul_f32_e32 v173, 0x3fb8aa3b, v173
	v_fma_f32 v174, v121, v174, 1.0
	v_exp_f32_e32 v173, v173
	v_mul_f32_e32 v174, v170, v174
	v_mul_f32_e32 v151, v126, v126
	v_mul_f32_e32 v175, v169, v174
	v_mul_f32_e32 v143, v142, v173
	v_mul_f32_e32 v159, v122, v175
	v_rcp_f32_e32 v176, v143
	v_mul_f32_e32 v169, v169, v143
	v_mul_f32_e32 v174, v174, v176
	v_mul_f32_e32 v134, v172, v176
	ds_write_b32 v166, v169 offset:17952
	ds_write_b32 v166, v174 offset:52768
	v_sub_f32_e32 v169, v52, v49
	v_sub_f32_e32 v170, v54, v53
	v_sub_f32_e32 v171, v56, v55
	v_fma_f32 v169, v169, v115, v49
	v_fma_f32 v170, v170, v116, v53
	v_fma_f32 v171, v171, v119, v55
	v_add_f32_e32 v172, v57, v117
	v_add_f32_e32 v173, v110, v118
	v_mul_f32_e32 v172, 0xbfb8aa3b, v172
	v_mul_f32_e32 v173, 0xbfb8aa3b, v173
	v_exp_f32_e32 v172, v172
	v_exp_f32_e32 v173, v173
	ds_write_b32 v167, v171 offset:768
	v_add_f32_e32 v172, 1.0, v172
	v_add_f32_e32 v173, 1.0, v173
	v_rcp_f32_e32 v172, v172
	v_rcp_f32_e32 v173, v173
	v_mul_f32_e32 v127, v170, v120
	v_mul_f32_e32 v173, 0xbf1b4598, v173
	v_add_f32_e32 v174, -1.0, v172
	v_mul_f32_e32 v173, 0x3fb8aa3b, v173
	v_fma_f32 v174, v121, v174, 1.0
	v_exp_f32_e32 v173, v173
	v_mul_f32_e32 v174, v170, v174
	v_mul_f32_e32 v153, v127, v127
	v_mul_f32_e32 v175, v169, v174
	v_mul_f32_e32 v144, v143, v173
	v_mul_f32_e32 v161, v122, v175
	v_rcp_f32_e32 v176, v144
	v_mul_f32_e32 v169, v169, v144
	v_mul_f32_e32 v174, v174, v176
	v_mul_f32_e32 v135, v172, v176
	ds_write_b32 v166, v169 offset:18224
	ds_write_b32 v166, v174 offset:53040
	v_sub_f32_e32 v169, v49, v60
	v_sub_f32_e32 v170, v53, v62
	v_sub_f32_e32 v171, v55, v64
	v_fma_f32 v169, v169, v115, v60
	v_fma_f32 v170, v170, v116, v62
	v_fma_f32 v171, v171, v119, v64
	v_add_f32_e32 v172, v66, v117
	v_add_f32_e32 v173, v111, v118
	v_mul_f32_e32 v172, 0xbfb8aa3b, v172
	v_mul_f32_e32 v173, 0xbfb8aa3b, v173
	v_exp_f32_e32 v172, v172
	v_exp_f32_e32 v173, v173
	ds_write_b32 v167, v171 offset:1024
	v_add_f32_e32 v172, 1.0, v172
	v_add_f32_e32 v173, 1.0, v173
	v_rcp_f32_e32 v172, v172
	v_rcp_f32_e32 v173, v173
	v_mul_f32_e32 v128, v170, v120
	v_mul_f32_e32 v173, 0xbf1b4598, v173
	v_add_f32_e32 v174, -1.0, v172
	v_mul_f32_e32 v173, 0x3fb8aa3b, v173
	v_fma_f32 v174, v121, v174, 1.0
	v_exp_f32_e32 v173, v173
	v_mul_f32_e32 v174, v170, v174
	v_mul_f32_e32 v154, v128, v128
	v_mul_f32_e32 v175, v169, v174
	v_mul_f32_e32 v145, v144, v173
	v_mul_f32_e32 v162, v122, v175
	v_rcp_f32_e32 v176, v145
	v_mul_f32_e32 v169, v169, v145
	v_mul_f32_e32 v174, v174, v176
	v_mul_f32_e32 v136, v172, v176
	ds_write_b32 v166, v169 offset:18496
	ds_write_b32 v166, v174 offset:53312
	v_sub_f32_e32 v169, v60, v59
	v_sub_f32_e32 v170, v62, v61
	v_sub_f32_e32 v171, v64, v63
	v_fma_f32 v169, v169, v115, v59
	v_fma_f32 v170, v170, v116, v61
	v_fma_f32 v171, v171, v119, v63
	v_add_f32_e32 v172, v65, v117
	v_add_f32_e32 v173, v112, v118
	v_mul_f32_e32 v172, 0xbfb8aa3b, v172
	v_mul_f32_e32 v173, 0xbfb8aa3b, v173
	v_exp_f32_e32 v172, v172
	v_exp_f32_e32 v173, v173
	ds_write_b32 v167, v171 offset:1280
	v_add_f32_e32 v172, 1.0, v172
	v_add_f32_e32 v173, 1.0, v173
	v_rcp_f32_e32 v172, v172
	v_rcp_f32_e32 v173, v173
	v_mul_f32_e32 v129, v170, v120
	v_mul_f32_e32 v173, 0xbf1b4598, v173
	v_add_f32_e32 v174, -1.0, v172
	v_mul_f32_e32 v173, 0x3fb8aa3b, v173
	v_fma_f32 v174, v121, v174, 1.0
	v_exp_f32_e32 v173, v173
	v_mul_f32_e32 v174, v170, v174
	v_mul_f32_e32 v156, v129, v129
	v_mul_f32_e32 v175, v169, v174
	v_mul_f32_e32 v146, v145, v173
	v_mul_f32_e32 v164, v122, v175
	v_rcp_f32_e32 v176, v146
	v_mul_f32_e32 v169, v169, v146
	v_mul_f32_e32 v174, v174, v176
	v_mul_f32_e32 v137, v172, v176
	ds_write_b32 v166, v169 offset:18768
	ds_write_b32 v166, v174 offset:53584
	v_sub_f32_e32 v169, v59, v67
	v_sub_f32_e32 v170, v61, v69
	v_sub_f32_e32 v171, v63, v71
	v_fma_f32 v169, v169, v115, v67
	v_fma_f32 v170, v170, v116, v69
	v_fma_f32 v171, v171, v119, v71
	v_add_f32_e32 v172, v74, v117
	v_add_f32_e32 v173, v113, v118
	v_mul_f32_e32 v172, 0xbfb8aa3b, v172
	v_mul_f32_e32 v173, 0xbfb8aa3b, v173
	v_exp_f32_e32 v172, v172
	v_exp_f32_e32 v173, v173
	ds_write_b32 v167, v171 offset:1536
	v_add_f32_e32 v172, 1.0, v172
	v_add_f32_e32 v173, 1.0, v173
	v_rcp_f32_e32 v172, v172
	v_rcp_f32_e32 v173, v173
	v_mul_f32_e32 v130, v170, v120
	v_mul_f32_e32 v173, 0xbf1b4598, v173
	v_add_f32_e32 v174, -1.0, v172
	v_mul_f32_e32 v173, 0x3fb8aa3b, v173
	v_fma_f32 v174, v121, v174, 1.0
	v_exp_f32_e32 v173, v173
	v_mul_f32_e32 v174, v170, v174
	v_mul_f32_e32 v155, v130, v130
	v_mul_f32_e32 v175, v169, v174
	v_mul_f32_e32 v147, v146, v173
	v_mul_f32_e32 v163, v122, v175
	v_rcp_f32_e32 v176, v147
	v_mul_f32_e32 v169, v169, v147
	v_mul_f32_e32 v174, v174, v176
	v_mul_f32_e32 v138, v172, v176
	ds_write_b32 v166, v169 offset:19040
	ds_write_b32 v166, v174 offset:53856
	v_sub_f32_e32 v169, v67, v68
	v_sub_f32_e32 v170, v69, v70
	v_sub_f32_e32 v171, v71, v72
	v_fma_f32 v169, v169, v115, v68
	v_fma_f32 v170, v170, v116, v70
	v_fma_f32 v171, v171, v119, v72
	v_add_f32_e32 v172, v73, v117
	v_add_f32_e32 v173, v114, v118
	v_mul_f32_e32 v172, 0xbfb8aa3b, v172
	v_mul_f32_e32 v173, 0xbfb8aa3b, v173
	v_exp_f32_e32 v172, v172
	v_exp_f32_e32 v173, v173
	ds_write_b32 v167, v171 offset:1792
	v_add_f32_e32 v172, 1.0, v172
	v_add_f32_e32 v173, 1.0, v173
	v_rcp_f32_e32 v172, v172
	v_rcp_f32_e32 v173, v173
	v_mul_f32_e32 v131, v170, v120
	v_mul_f32_e32 v173, 0xbf1b4598, v173
	v_add_f32_e32 v174, -1.0, v172
	v_mul_f32_e32 v173, 0x3fb8aa3b, v173
	v_fma_f32 v174, v121, v174, 1.0
	v_exp_f32_e32 v173, v173
	v_mul_f32_e32 v174, v170, v174
	v_mul_f32_e32 v157, v131, v131
	v_mul_f32_e32 v175, v169, v174
	v_mul_f32_e32 v148, v147, v173
	v_mul_f32_e32 v165, v122, v175
	v_rcp_f32_e32 v176, v148
	v_mul_f32_e32 v169, v169, v148
	v_mul_f32_e32 v174, v174, v176
	v_mul_f32_e32 v139, v172, v176
	ds_write_b32 v166, v169 offset:19312
	ds_write_b32 v166, v174 offset:54128
	v_permlane32_swap_b32_e32 v150, v151
	v_permlane32_swap_b32_e32 v152, v153
	v_permlane32_swap_b32_e32 v154, v155
	v_permlane32_swap_b32_e32 v156, v157
	v_permlane32_swap_b32_e32 v158, v159
	v_permlane32_swap_b32_e32 v160, v161
	v_permlane32_swap_b32_e32 v162, v163
	v_permlane32_swap_b32_e32 v164, v165
	v_add_f32_e32 v182, v150, v151
	v_add_f32_e32 v183, v152, v153
	v_add_f32_e32 v184, v154, v155
	v_add_f32_e32 v185, v156, v157
	v_add_f32_e32 v186, v158, v159
	v_add_f32_e32 v187, v160, v161
	v_add_f32_e32 v188, v162, v163
	v_add_f32_e32 v189, v164, v165
	v_permlane16_swap_b32_e32 v182, v183
	v_permlane16_swap_b32_e32 v184, v185
	v_permlane16_swap_b32_e32 v186, v187
	v_permlane16_swap_b32_e32 v188, v189
	v_add_f32_e32 v190, v182, v183
	v_add_f32_e32 v191, v184, v185
	v_add_f32_e32 v192, v186, v187
	v_add_f32_e32 v193, v188, v189
	v_add_f32_dpp v194, v190, v190 row_mirror row_mask:0xf bank_mask:0x3
	v_add_f32_dpp v194, v191, v191 row_mirror row_mask:0xf bank_mask:0xc
	v_add_f32_dpp v195, v192, v192 row_mirror row_mask:0xf bank_mask:0x3
	v_add_f32_dpp v195, v193, v193 row_mirror row_mask:0xf bank_mask:0xc
	v_add_f32_dpp v196, v194, v194 row_half_mirror row_mask:0xf bank_mask:0x5
	s_nop 0
	v_add_f32_dpp v196, v195, v195 row_half_mirror row_mask:0xf bank_mask:0xa
	s_nop 1
	v_add_f32_dpp v196, v196, v196 quad_perm:[1,0,3,2] row_mask:0xf bank_mask:0xf
	s_nop 1
	v_add_f32_dpp v196, v196, v196 quad_perm:[2,3,0,1] row_mask:0xf bank_mask:0xf
	v_add_f32_e32 v197, 0x2b8cbccc, v196
	v_lshrrev_b32_e32 v198, 4, v76
	v_rsq_f32_e32 v197, v197
	v_bfe_u32 v168, v76, 3, 1
	v_lshl_add_u32 v198, v168, 2, v198
	v_add_u32_e32 v198, v198, v26
	v_lshl_add_u32 v198, v198, 2, s16
	s_mov_b32 s4, 0x10101010
	s_mov_b32 s5, 0x10101010
	s_mov_b64 exec, s[4:5]
	ds_write_b32 v198, v196
	s_mov_b64 exec, -1
	v_readlane_b32 s0, v197, 0
	v_readlane_b32 s1, v197, 16
	v_readlane_b32 s3, v197, 32
	v_readlane_b32 s4, v197, 48
	v_mul_f32_e32 v124, s0, v124
	v_mul_f32_e32 v125, s1, v125
	v_mul_f32_e32 v126, s3, v126
	v_mul_f32_e32 v127, s4, v127
	v_mul_f32_e64 v169, v124, -v140
	v_mul_f32_e32 v132, v124, v132
	v_mul_f32_e64 v170, v125, -v141
	v_mul_f32_e32 v133, v125, v133
	v_mul_f32_e64 v171, v126, -v142
	v_mul_f32_e32 v134, v126, v134
	v_mul_f32_e64 v172, v127, -v143
	v_mul_f32_e32 v135, v127, v135
	ds_write_b32 v166, v169 offset:0
	ds_write_b32 v166, v132 offset:34816
	ds_write_b32 v166, v170 offset:272
	ds_write_b32 v166, v133 offset:35088
	ds_write_b32 v166, v171 offset:544
	ds_write_b32 v166, v134 offset:35360
	ds_write_b32 v166, v172 offset:816
	ds_write_b32 v166, v135 offset:35632
	v_readlane_b32 s0, v197, 8
	v_readlane_b32 s1, v197, 24
	v_readlane_b32 s3, v197, 40
	v_readlane_b32 s4, v197, 56
	v_mul_f32_e32 v128, s0, v128
	v_mul_f32_e32 v129, s1, v129
	v_mul_f32_e32 v130, s3, v130
	v_mul_f32_e32 v131, s4, v131
	v_mul_f32_e64 v169, v128, -v144
	v_mul_f32_e32 v136, v128, v136
	v_mul_f32_e64 v170, v129, -v145
	v_mul_f32_e32 v137, v129, v137
	v_mul_f32_e64 v171, v130, -v146
	v_mul_f32_e32 v138, v130, v138
	v_mul_f32_e64 v172, v131, -v147
	v_mul_f32_e32 v139, v131, v139
	ds_write_b32 v166, v169 offset:1088
	ds_write_b32 v166, v136 offset:35904
	ds_write_b32 v166, v170 offset:1360
	ds_write_b32 v166, v137 offset:36176
	ds_write_b32 v166, v171 offset:1632
	ds_write_b32 v166, v138 offset:36448
	ds_write_b32 v166, v172 offset:1904
	ds_write_b32 v166, v139 offset:36720
	v_lshlrev_b32_e32 v168, 8, v78
	v_lshl_add_u32 v168, v76, 2, v168
	v_add_u32_e32 v168, 0x11000, v168
	ds_write_b32 v168, v148
	ds_read_b128 v[136:139], v79 offset:0
	ds_read_b128 v[152:155], v79 offset:34816
	ds_read_b128 v[140:143], v79 offset:64
	ds_read_b128 v[156:159], v79 offset:34880
	ds_read_b128 v[144:147], v79 offset:128
	ds_read_b128 v[160:163], v79 offset:34944
	ds_read_b128 v[148:151], v79 offset:192
	ds_read_b128 v[164:167], v79 offset:35008
	v_cmp_ge_u32_e64 s[0:1], 1, v87
	v_cmp_ge_u32_e64 s[4:5], 2, v87
	v_cmp_ge_u32_e64 s[6:7], 3, v87
	v_cmp_ge_u32_e32 vcc, 0, v87
	s_waitcnt lgkmcnt(0)
	v_mfma_f32_16x16x4_f32 v[36:39], v136, v152, 0
	v_mfma_f32_16x16x4_f32 v[40:43], v137, v153, 0
	v_mfma_f32_16x16x4_f32 v[36:39], v138, v154, v[36:39]
	v_mfma_f32_16x16x4_f32 v[40:43], v139, v155, v[40:43]
	v_mfma_f32_16x16x4_f32 v[36:39], v140, v156, v[36:39]
	v_mfma_f32_16x16x4_f32 v[40:43], v141, v157, v[40:43]
	v_mfma_f32_16x16x4_f32 v[36:39], v142, v158, v[36:39]
	v_mfma_f32_16x16x4_f32 v[40:43], v143, v159, v[40:43]
	v_mfma_f32_16x16x4_f32 v[36:39], v144, v160, v[36:39]
	v_mfma_f32_16x16x4_f32 v[40:43], v145, v161, v[40:43]
	v_mfma_f32_16x16x4_f32 v[36:39], v146, v162, v[36:39]
	v_mfma_f32_16x16x4_f32 v[40:43], v147, v163, v[40:43]
	v_mfma_f32_16x16x4_f32 v[36:39], v148, v164, v[36:39]
	v_mfma_f32_16x16x4_f32 v[40:43], v149, v165, v[40:43]
	v_mfma_f32_16x16x4_f32 v[36:39], v150, v166, v[36:39]
	v_mfma_f32_16x16x4_f32 v[40:43], v151, v167, v[40:43]
	s_nop 7
	s_nop 2
	v_pk_add_f32 v[36:37], v[36:37], v[40:41]
	v_pk_add_f32 v[38:39], v[38:39], v[42:43]
	v_cndmask_b32_e32 v36, 0, v36, vcc
	v_cndmask_b32_e64 v37, 0, v37, s[0:1]
	v_cndmask_b32_e64 v38, 0, v38, s[4:5]
	v_cndmask_b32_e64 v39, 0, v39, s[6:7]
	ds_write_b32 v86, v36 offset:0
	ds_write_b32 v86, v37 offset:32
	ds_write_b32 v86, v38 offset:64
	ds_write_b32 v86, v39 offset:96
	ds_read_b128 v[124:127], v92 offset:32
	ds_read_b128 v[128:131], v92 offset:64
	ds_read_b128 v[132:135], v92 offset:96
	ds_read_b128 v[136:139], v92 offset:128
	ds_read_b128 v[144:147], v92 offset:160
	ds_read_b128 v[148:151], v92 offset:176
	ds_read_b128 v[152:155], v92 offset:192
	ds_read_b128 v[156:159], v92 offset:208
	ds_read_b128 v[160:163], v92 offset:224
	ds_read_b128 v[164:167], v92 offset:240
	ds_read_b128 v[182:185], v93 offset:512
	ds_read_b128 v[186:189], v93 offset:528
	ds_read_b128 v[190:193], v93 offset:544
	ds_read_b128 v[194:197], v93 offset:560
	v_cmp_eq_u32_e32 vcc, 0, v102
	v_cndmask_b32_e32 v36, 0, v103, vcc
	v_cmp_eq_u32_e32 vcc, 1, v102
	v_cndmask_b32_e32 v37, 0, v103, vcc
	v_cmp_eq_u32_e32 vcc, 2, v102
	v_cndmask_b32_e32 v38, 0, v103, vcc
	v_cmp_eq_u32_e32 vcc, 3, v102
	v_cndmask_b32_e32 v39, 0, v103, vcc
	v_cmp_eq_u32_e32 vcc, 4, v102
	v_cndmask_b32_e32 v40, 0, v103, vcc
	v_cmp_eq_u32_e32 vcc, 5, v102
	v_cndmask_b32_e32 v41, 0, v103, vcc
	v_cmp_eq_u32_e32 vcc, 6, v102
	v_cndmask_b32_e32 v42, 0, v103, vcc
	v_cmp_eq_u32_e32 vcc, 7, v102
	v_cndmask_b32_e32 v43, 0, v103, vcc
	s_waitcnt lgkmcnt(0)
	v_fmac_f32_e32 v37, v124, v36
	v_fmac_f32_e32 v38, v128, v36
	v_fmac_f32_e32 v39, v132, v36
	v_fmac_f32_e32 v40, v136, v36
	v_fmac_f32_e32 v41, v144, v36
	v_fmac_f32_e32 v42, v152, v36
	v_fmac_f32_e32 v43, v160, v36
	v_fmac_f32_e32 v38, v129, v37
	v_fmac_f32_e32 v39, v133, v37
	v_fmac_f32_e32 v40, v137, v37
	v_fmac_f32_e32 v41, v145, v37
	v_fmac_f32_e32 v42, v153, v37
	v_fmac_f32_e32 v43, v161, v37
	v_fmac_f32_e32 v39, v134, v38
	v_fmac_f32_e32 v40, v138, v38
	v_fmac_f32_e32 v41, v146, v38
	v_fmac_f32_e32 v42, v154, v38
	v_fmac_f32_e32 v43, v162, v38
	v_fmac_f32_e32 v40, v139, v39
	v_fmac_f32_e32 v41, v147, v39
	v_fmac_f32_e32 v42, v155, v39
	v_fmac_f32_e32 v43, v163, v39
	v_fmac_f32_e32 v41, v148, v40
	v_fmac_f32_e32 v42, v156, v40
	v_fmac_f32_e32 v43, v164, v40
	v_fmac_f32_e32 v42, v157, v41
	v_fmac_f32_e32 v43, v165, v41
	v_fmac_f32_e32 v43, v166, v42
	v_mul_f32_e32 v198, v182, v36
	v_fmac_f32_e32 v198, v183, v37
	v_fmac_f32_e32 v198, v184, v38
	v_fmac_f32_e32 v198, v185, v39
	v_fmac_f32_e32 v198, v186, v40
	v_fmac_f32_e32 v198, v187, v41
	v_fmac_f32_e32 v198, v188, v42
	v_fmac_f32_e32 v198, v189, v43
	v_mul_f32_e32 v199, v190, v36
	v_fmac_f32_e32 v199, v191, v37
	v_fmac_f32_e32 v199, v192, v38
	v_fmac_f32_e32 v199, v193, v39
	v_fmac_f32_e32 v199, v194, v40
	v_fmac_f32_e32 v199, v195, v41
	v_fmac_f32_e32 v199, v196, v42
	v_fmac_f32_e32 v199, v197, v43
	ds_write_b32 v100, v36 offset:0
	ds_write_b32 v100, v37 offset:32
	ds_write_b32 v100, v38 offset:64
	ds_write_b32 v100, v39 offset:96
	ds_write_b32 v100, v40 offset:128
	ds_write_b32 v100, v41 offset:160
	ds_write_b32 v100, v42 offset:192
	ds_write_b32 v100, v43 offset:224
	ds_write_b32 v101, v198 offset:512
	ds_write_b32 v101, v199 offset:544
	s_lshl_b32 s17, s40, 6
	s_cmp_lg_u32 s40, 31
	s_waitcnt lgkmcnt(0)
	s_barrier
	s_cbranch_scc0 .LBB0_586
	v_readfirstlane_b32 s0, v180
	s_nop 1
	s_cmpk_ge_u32 s0, 0x100
	s_cbranch_scc1 .LBB0_586
	v_readfirstlane_b32 s0, v78
	v_lshlrev_b32_e32 v2, 1, v28
	v_lshlrev_b32_e32 v3, 2, v28
	s_lshl_b32 s0, s0, 3
	s_add_i32 s0, s0, s17
	s_add_i32 s0, s0, 64
	s_add_u32 s0, s80, s0
	s_mul_i32 s1, s0, s83
	s_add_u32 s4, s46, s1
	s_addc_u32 s5, s47, 0
	s_lshl_b32 s1, s0, 10
	s_add_u32 s6, s62, s1
	s_addc_u32 s7, s63, 0
	s_lshl_b32 s1, s0, 11
	s_add_u32 s10, s34, s1
	s_addc_u32 s11, s35, 0
	global_load_short_d16_hi v106, v2, s[4:5] offset:-3072
	global_load_short_d16_hi v35, v2, s[4:5] offset:-2048
	global_load_short_d16_hi v34, v2, s[4:5] offset:-1024
	global_load_short_d16_hi v44, v2, s[4:5]
	global_load_short_d16_hi v46, v2, s[4:5] offset:1024
	global_load_short_d16_hi v48, v2, s[4:5] offset:2048
	s_add_u32 s4, s4, s83
	s_addc_u32 s5, s5, 0
	global_load_short_d16_hi v50, v2, s[6:7]
	global_load_dword v107, v3, s[10:11]
	global_load_short_d16_hi v1, v2, s[4:5]
	global_load_short_d16_hi v45, v2, s[4:5] offset:1024
	global_load_short_d16_hi v47, v2, s[4:5] offset:2048
	s_add_u32 s4, s4, s83
	s_addc_u32 s5, s5, 0
	global_load_short_d16_hi v51, v2, s[6:7] offset:1024
	global_load_dword v108, v3, s[10:11] offset:2048
	s_add_u32 s10, s10, 0x1000
	s_addc_u32 s11, s11, 0
	global_load_short_d16_hi v52, v2, s[4:5]
	global_load_short_d16_hi v54, v2, s[4:5] offset:1024
	global_load_short_d16_hi v56, v2, s[4:5] offset:2048
	s_add_u32 s4, s4, s83
	s_addc_u32 s5, s5, 0
	global_load_short_d16_hi v58, v2, s[6:7] offset:2048
	global_load_dword v109, v3, s[10:11]
	global_load_short_d16_hi v49, v2, s[4:5]
	global_load_short_d16_hi v53, v2, s[4:5] offset:1024
	global_load_short_d16_hi v55, v2, s[4:5] offset:2048
	s_add_u32 s4, s4, s83
	s_addc_u32 s5, s5, 0
	global_load_short_d16_hi v57, v2, s[6:7] offset:3072
	s_add_u32 s6, s6, 0x1000
	s_addc_u32 s7, s7, 0
	global_load_dword v110, v3, s[10:11] offset:2048
	s_add_u32 s10, s10, 0x1000
	s_addc_u32 s11, s11, 0
	global_load_short_d16_hi v60, v2, s[4:5]
	global_load_short_d16_hi v62, v2, s[4:5] offset:1024
	global_load_short_d16_hi v64, v2, s[4:5] offset:2048
	s_add_u32 s4, s4, s83
	s_addc_u32 s5, s5, 0
	global_load_short_d16_hi v66, v2, s[6:7]
	global_load_dword v111, v3, s[10:11]
	global_load_short_d16_hi v59, v2, s[4:5]
	global_load_short_d16_hi v61, v2, s[4:5] offset:1024
	global_load_short_d16_hi v63, v2, s[4:5] offset:2048
	s_add_u32 s4, s4, s83
	s_addc_u32 s5, s5, 0
	global_load_short_d16_hi v65, v2, s[6:7] offset:1024
	global_load_dword v112, v3, s[10:11] offset:2048
	s_add_u32 s10, s10, 0x1000
	s_addc_u32 s11, s11, 0
	global_load_short_d16_hi v67, v2, s[4:5]
	global_load_short_d16_hi v69, v2, s[4:5] offset:1024
	global_load_short_d16_hi v71, v2, s[4:5] offset:2048
	s_add_u32 s4, s4, s83
	s_addc_u32 s5, s5, 0
	global_load_short_d16_hi v74, v2, s[6:7] offset:2048
	global_load_dword v113, v3, s[10:11]
	global_load_short_d16_hi v68, v2, s[4:5]
	global_load_short_d16_hi v70, v2, s[4:5] offset:1024
	global_load_short_d16_hi v72, v2, s[4:5] offset:2048
	global_load_short_d16_hi v73, v2, s[6:7] offset:3072
	global_load_dword v114, v3, s[10:11] offset:2048

.Lrw_go_0:
	s_waitcnt vmcnt(0)
	ds_read2st64_b32 v[150:151], v146 offset0:0 offset1:4
	ds_read2st64_b32 v[152:153], v147 offset0:0 offset1:4
	ds_read2_b32 v[154:155], v148 offset0:0 offset1:4
	v_lshlrev_b32_e32 v128, 16, v128
	v_lshlrev_b32_e32 v129, 16, v129
	s_waitcnt lgkmcnt(0)
	v_pk_mov_b32 v[156:157], v[150:151], v[150:151] op_sel:[0,1]
	s_nop 1
	v_permlane32_swap_b32_e32 v156, v157
	v_add_f32_e32 v156, v156, v157
	v_pk_mul_f32 v[162:163], v[128:129], s[8:9] op_sel_hi:[1,0]
	v_exp_f32_e32 v162, v162
	v_add_f32_dpp v156, v156, v156 quad_perm:[1,0,3,2] row_mask:0xf bank_mask:0xf bound_ctrl:1
	v_exp_f32_e32 v163, v163
	s_nop 0
	v_add_f32_dpp v156, v156, v156 quad_perm:[2,3,0,1] row_mask:0xf bank_mask:0xf bound_ctrl:1
	s_nop 0
	s_nop 0
	v_add_f32_dpp v156, v156, v156 row_half_mirror row_mask:0xf bank_mask:0xf bound_ctrl:1
	s_nop 0
	s_nop 0
	v_add_f32_dpp v156, v156, v156 row_mirror row_mask:0xf bank_mask:0xf bound_ctrl:1
	s_nop 0
	s_nop 0
	v_add_f32_dpp v156, v156, v156 row_bcast:15 row_mask:0xa bank_mask:0xf
	s_nop 0
	v_readlane_b32 s4, v156, 31
	v_readlane_b32 s5, v156, 63
	s_nop 1
	v_pk_fma_f32 v[150:151], s[4:5], v[124:125], v[150:151] op_sel:[0,1,0] op_sel_hi:[1,1,1]
	v_pk_mul_f32 v[158:159], v[150:151], v[150:151]
	s_nop 1
	v_permlane32_swap_b32_e32 v158, v159
	v_add_f32_e32 v158, v158, v159
	v_pk_add_f32 v[162:163], v[162:163], 1.0 op_sel_hi:[1,0]
	v_rcp_f32_e32 v162, v162
	v_add_f32_dpp v158, v158, v158 quad_perm:[1,0,3,2] row_mask:0xf bank_mask:0xf bound_ctrl:1
	v_rcp_f32_e32 v163, v163
	s_nop 0
	v_add_f32_dpp v158, v158, v158 quad_perm:[2,3,0,1] row_mask:0xf bank_mask:0xf bound_ctrl:1
	s_nop 0
	s_nop 0
	v_add_f32_dpp v158, v158, v158 row_half_mirror row_mask:0xf bank_mask:0xf bound_ctrl:1
	s_nop 0
	s_nop 0
	v_add_f32_dpp v158, v158, v158 row_mirror row_mask:0xf bank_mask:0xf bound_ctrl:1
	s_nop 0
	s_nop 0
	v_add_f32_dpp v158, v158, v158 row_bcast:15 row_mask:0xa bank_mask:0xf
	s_nop 0
	v_readlane_b32 s6, v158, 31
	v_readlane_b32 s7, v158, 63
	s_nop 1
	v_pk_fma_f32 v[160:161], s[6:7], v[126:127], v[126:127] op_sel:[0,0,1] op_sel_hi:[1,0,1]
	v_rsq_f32_e32 v160, v160
	v_rsq_f32_e32 v161, v161
	s_nop 0
	v_pk_mul_f32 v[164:165], v[150:151], v[160:161]
	v_pk_fma_f32 v[164:165], v[144:145], v[164:165], v[144:145] op_sel:[0,0,1] op_sel_hi:[0,1,1]
	v_pk_fma_f32 v[164:165], v[154:155], v[152:153], v[164:165]
	v_pk_mul_f32 v[164:165], v[164:165], v[128:129]
	v_pk_mul_f32 v[164:165], v[162:163], v[164:165]
	v_bfe_u32 v156, v164, 16, 1
	v_add3_u32 v164, v164, v156, s97
	v_bfe_u32 v157, v165, 16, 1
	v_add3_u32 v165, v165, v157, s97
	global_store_short_d16_hi v124, v164, s[12:13]
	s_add_u32 s12, s12, 0x1000
	s_addc_u32 s13, s13, 0
	global_store_short_d16_hi v124, v165, s[12:13]
	s_add_u32 s12, s12, 0x1000
	s_addc_u32 s13, s13, 0
	s_cmp_lg_u32 s40, 31
	s_cbranch_scc0 .Lrw_nopf
	v_readfirstlane_b32 s0, v78
	v_lshlrev_b32_e32 v2, 1, v28
	v_lshlrev_b32_e32 v3, 2, v28
	s_lshl_b32 s0, s0, 3
	s_add_i32 s0, s0, s17
	s_add_i32 s0, s0, 64
	s_add_u32 s0, s80, s0
	s_mul_i32 s1, s0, s83
	s_add_u32 s4, s46, s1
	s_addc_u32 s5, s47, 0
	s_lshl_b32 s1, s0, 10
	s_add_u32 s6, s62, s1
	s_addc_u32 s7, s63, 0
	s_lshl_b32 s1, s0, 11
	s_add_u32 s10, s34, s1
	s_addc_u32 s11, s35, 0
	global_load_short_d16_hi v106, v2, s[4:5] offset:-3072
	global_load_short_d16_hi v35, v2, s[4:5] offset:-2048
	global_load_short_d16_hi v34, v2, s[4:5] offset:-1024
	global_load_short_d16_hi v44, v2, s[4:5]
	global_load_short_d16_hi v46, v2, s[4:5] offset:1024
	global_load_short_d16_hi v48, v2, s[4:5] offset:2048
	s_add_u32 s4, s4, s83
	s_addc_u32 s5, s5, 0
	global_load_short_d16_hi v50, v2, s[6:7]
	global_load_dword v107, v3, s[10:11]
	global_load_short_d16_hi v1, v2, s[4:5]
	global_load_short_d16_hi v45, v2, s[4:5] offset:1024
	global_load_short_d16_hi v47, v2, s[4:5] offset:2048
	s_add_u32 s4, s4, s83
	s_addc_u32 s5, s5, 0
	global_load_short_d16_hi v51, v2, s[6:7] offset:1024
	global_load_dword v108, v3, s[10:11] offset:2048
	s_add_u32 s10, s10, 0x1000
	s_addc_u32 s11, s11, 0
	global_load_short_d16_hi v52, v2, s[4:5]
	global_load_short_d16_hi v54, v2, s[4:5] offset:1024
	global_load_short_d16_hi v56, v2, s[4:5] offset:2048
	s_add_u32 s4, s4, s83
	s_addc_u32 s5, s5, 0
	global_load_short_d16_hi v58, v2, s[6:7] offset:2048
	global_load_dword v109, v3, s[10:11]
	global_load_short_d16_hi v49, v2, s[4:5]
	global_load_short_d16_hi v53, v2, s[4:5] offset:1024
	global_load_short_d16_hi v55, v2, s[4:5] offset:2048
	s_add_u32 s4, s4, s83
	s_addc_u32 s5, s5, 0
	global_load_short_d16_hi v57, v2, s[6:7] offset:3072
	s_add_u32 s6, s6, 0x1000
	s_addc_u32 s7, s7, 0
	global_load_dword v110, v3, s[10:11] offset:2048
	s_add_u32 s10, s10, 0x1000
	s_addc_u32 s11, s11, 0
	global_load_short_d16_hi v60, v2, s[4:5]
	global_load_short_d16_hi v62, v2, s[4:5] offset:1024
	global_load_short_d16_hi v64, v2, s[4:5] offset:2048
	s_add_u32 s4, s4, s83
	s_addc_u32 s5, s5, 0
	global_load_short_d16_hi v66, v2, s[6:7]
	global_load_dword v111, v3, s[10:11]
	global_load_short_d16_hi v59, v2, s[4:5]
	global_load_short_d16_hi v61, v2, s[4:5] offset:1024
	global_load_short_d16_hi v63, v2, s[4:5] offset:2048
	s_add_u32 s4, s4, s83
	s_addc_u32 s5, s5, 0
	global_load_short_d16_hi v65, v2, s[6:7] offset:1024
	global_load_dword v112, v3, s[10:11] offset:2048
	s_add_u32 s10, s10, 0x1000
	s_addc_u32 s11, s11, 0
	global_load_short_d16_hi v67, v2, s[4:5]
	global_load_short_d16_hi v69, v2, s[4:5] offset:1024
	global_load_short_d16_hi v71, v2, s[4:5] offset:2048
	s_add_u32 s4, s4, s83
	s_addc_u32 s5, s5, 0
	global_load_short_d16_hi v74, v2, s[6:7] offset:2048
	global_load_dword v113, v3, s[10:11]
	global_load_short_d16_hi v68, v2, s[4:5]
	global_load_short_d16_hi v70, v2, s[4:5] offset:1024
	global_load_short_d16_hi v72, v2, s[4:5] offset:2048
	global_load_short_d16_hi v73, v2, s[6:7] offset:3072
	global_load_dword v114, v3, s[10:11] offset:2048
